# HGRN2 prompt recurrence: compute waves yield ~1us (s_sleep) at the top of every chunk so the loader waves sharing their SIMDs issue the next chunk loads and LDS writes unobstructed
# speedup vs baseline: 1.0035x; 1.0035x over previous
.LBB0_989:
	s_sleep 37
	s_add_i32 s63, s64, 0xffffff80
	s_and_b32 s63, s63, 0x80
	v_lshl_add_u32 v20, s63, 2, v135
	ds_read2_b32 v[18:19], v20 offset1:32
	ds_read2_b32 v[20:21], v20 offset0:64 offset1:96
	s_mul_i32 s62, s66, 0xab
	s_bfe_u32 s62, s62, 0x70009
	s_mul_i32 s62, s62, 3
	s_waitcnt lgkmcnt(1)
	v_mov_b32_e32 v22, v18
	s_waitcnt lgkmcnt(0)
	v_mov_b32_e32 v23, v20
	v_mov_b32_e32 v20, v19
	v_pk_add_f32 v[18:19], v[22:23], v[20:21]
	s_sub_i32 s62, s66, s62
	v_add_f32_e32 v18, v18, v19
	v_fmamk_f32 v18, v18, 0x3c000000, v208
	v_mul_f32_e32 v19, 0x4b800000, v18
	v_cmp_gt_f32_e32 vcc, s71, v18
	v_ashrrev_i32_e32 v199, 31, v198
	s_and_b32 s62, s62, 0xff
	v_cndmask_b32_e32 v18, v18, v19, vcc
	v_rsq_f32_e32 v18, v18
	s_mul_i32 s62, s62, 0x8400
	s_add_i32 s62, s62, 0
	v_lshl_add_u32 v212, v137, 4, s62
	v_mul_f32_e32 v19, 0x45800000, v18
	v_cndmask_b32_e32 v50, v18, v19, vcc
	v_lshlrev_b64 v[18:19], 12, v[198:199]
	v_pk_mul_f32 v[2:3], v[2:3], v[50:51] op_sel_hi:[1,0]
	v_lshl_add_u64 v[200:201], v[188:189], 0, v[18:19]
	s_waitcnt vmcnt(7)
	v_pk_mul_f32 v[2:3], v[94:95], v[2:3]
	s_waitcnt vmcnt(3)
	v_lshlrev_b32_e32 v18, 16, v192
	v_and_b32_e32 v19, 0xffff0000, v192
	v_pk_mul_f32 v[2:3], v[2:3], v[18:19]
	ds_read_b128 v[214:217], v212
	v_cvt_pk_bf16_f32 v18, v2, v3
	v_pk_mul_f32 v[2:3], v[4:5], v[50:51] op_sel_hi:[1,0]
	v_lshlrev_b32_e32 v22, 16, v193
	v_pk_mul_f32 v[20:21], v[96:97], v[2:3]
	ds_read_b128 v[2:5], v212 offset:8192
	v_and_b32_e32 v23, 0xffff0000, v193
	v_pk_mul_f32 v[20:21], v[20:21], v[22:23]
	v_pk_mul_f32 v[12:13], v[12:13], v[50:51] op_sel_hi:[1,0]
	v_cvt_pk_bf16_f32 v19, v20, v21
	global_store_dwordx2 v[200:201], v[18:19], off
	s_waitcnt lgkmcnt(0)
	v_mfma_f32_32x32x16_bf16 v[18:33], v[2:5], v[214:217], 0
	ds_read_b128 v[34:37], v212 offset:9216
	ds_read_b128 v[218:221], v212 offset:1024
	v_mul_f32_e64 v2, v6, v50
	v_mul_f32_e64 v3, v7, v50
	s_waitcnt vmcnt(3)
	v_lshlrev_b32_e32 v4, 16, v190
	v_pk_mul_f32 v[2:3], v[90:91], v[2:3]
	v_and_b32_e32 v5, 0xffff0000, v190
	v_pk_mul_f32 v[2:3], v[2:3], v[4:5]
	ds_read_b128 v[222:225], v212 offset:2048
	v_cvt_pk_bf16_f32 v38, v2, v3
	ds_read_b128 v[2:5], v212 offset:10240
	s_waitcnt lgkmcnt(2)
	v_mfma_f32_32x32x16_bf16 v[18:33], v[34:37], v[218:221], v[18:33]
	v_mul_f32_e64 v6, v8, v50
	v_mul_f32_e64 v7, v9, v50
	v_lshlrev_b32_e32 v36, 16, v191
	v_mul_f32_e64 v34, v92, v6
	v_mul_f32_e64 v35, v93, v7
	ds_read_b128 v[6:9], v212 offset:11264
	ds_read_b128 v[238:241], v212 offset:3072
	v_and_b32_e32 v37, 0xffff0000, v191
	ds_read_b128 v[46:49], v212 offset:4096
	v_add_u32_e32 v199, s62, v139
	s_waitcnt lgkmcnt(3)
	v_mfma_f32_32x32x16_bf16 v[18:33], v[2:5], v[222:225], v[18:33]
	v_mul_f32_e64 v2, v34, v36
	v_mul_f32_e64 v3, v35, v37
	s_waitcnt vmcnt(2)
	v_lshlrev_b32_e32 v34, 16, v186
	v_cvt_pk_bf16_f32 v39, v2, v3
	v_pk_mul_f32 v[2:3], v[10:11], v[50:51] op_sel_hi:[1,0]
	v_and_b32_e32 v35, 0xffff0000, v186
	v_pk_mul_f32 v[10:11], v[86:87], v[2:3]
	ds_read_b128 v[2:5], v212 offset:12288
	s_waitcnt lgkmcnt(2)
	v_mfma_f32_32x32x16_bf16 v[18:33], v[6:9], v[238:241], v[18:33]
	global_store_dwordx2 v[200:201], v[38:39], off offset:16
	v_mul_f32_e64 v6, v10, v34
	v_mul_f32_e64 v7, v11, v35
	v_add_u32_e32 v198, 32, v198
	v_cvt_pk_bf16_f32 v10, v6, v7
	ds_read_b128 v[6:9], v212 offset:13312
	ds_read_b128 v[42:45], v212 offset:5120
	ds_read_b128 v[38:41], v212 offset:6144
	s_waitcnt lgkmcnt(3)
	v_mfma_f32_32x32x16_bf16 v[18:33], v[2:5], v[46:49], v[18:33]
	v_mul_f32_e64 v2, v88, v12
	v_mul_f32_e64 v3, v89, v13
	v_lshlrev_b32_e32 v4, 16, v187
	v_and_b32_e32 v5, 0xffff0000, v187
	v_mul_f32_e64 v2, v2, v4
	v_mul_f32_e64 v3, v3, v5
	s_waitcnt vmcnt(2)
	v_lshlrev_b32_e32 v12, 16, v184
	v_cvt_pk_bf16_f32 v11, v2, v3
	ds_read_b128 v[2:5], v212 offset:14336
	s_waitcnt lgkmcnt(2)
	v_mfma_f32_32x32x16_bf16 v[18:33], v[6:9], v[42:45], v[18:33]
	global_store_dwordx2 v[200:201], v[10:11], off offset:32
	v_mul_f32_e64 v6, v14, v50
	v_mul_f32_e64 v7, v15, v50
	v_and_b32_e32 v13, 0xffff0000, v184
	v_mul_f32_e64 v10, v82, v6
	v_mul_f32_e64 v11, v83, v7
	ds_read_b128 v[6:9], v212 offset:15360
	ds_read_b128 v[34:37], v212 offset:7168
	s_waitcnt lgkmcnt(2)
	v_mfma_f32_32x32x16_bf16 v[18:33], v[2:5], v[38:41], v[18:33]
	v_mul_f32_e64 v2, v10, v12
	v_mul_f32_e64 v3, v11, v13
	v_add_u32_e32 v10, s68, v212
	ds_read_b128 v[54:57], v10 offset:24576
	v_cvt_pk_bf16_f32 v184, v2, v3
	v_pk_mul_f32 v[2:3], v[16:17], v[50:51] op_sel_hi:[1,0]
	v_lshlrev_b32_e32 v4, 16, v185
	v_pk_mul_f32 v[2:3], v[84:85], v[2:3]
	s_waitcnt lgkmcnt(1)
	v_mfma_f32_32x32x16_bf16 v[18:33], v[6:9], v[34:37], v[18:33]
	v_and_b32_e32 v5, 0xffff0000, v185
	v_mul_f32_e64 v186, v2, v4
	v_mul_f32_e64 v187, v3, v5
	ds_read_b128 v[50:53], v10 offset:28672
	v_cvt_pk_bf16_f32 v185, v186, v187
	s_nop 6
	v_cndmask_b32_e64 v2, v18, 0, s[6:7]
	v_cndmask_b32_e64 v3, 0, v19, s[8:9]
	v_cndmask_b32_e64 v4, v20, 0, s[10:11]
	v_cndmask_b32_e64 v5, v21, 0, s[12:13]
	v_cndmask_b32_e64 v6, v22, 0, s[14:15]
	v_cndmask_b32_e64 v7, v23, 0, s[16:17]
	v_cndmask_b32_e64 v8, v24, 0, s[18:19]
	v_cndmask_b32_e64 v9, v25, 0, s[20:21]
	v_cvt_pk_bf16_f32 v2, v2, v3
	v_cvt_pk_bf16_f32 v3, v4, v5
	v_cvt_pk_bf16_f32 v4, v6, v7
	v_cvt_pk_bf16_f32 v5, v8, v9
	v_cndmask_b32_e64 v18, v26, 0, s[22:23]
	v_cndmask_b32_e64 v19, v27, 0, s[24:25]
	s_waitcnt lgkmcnt(1)
	v_mfma_f32_32x32x16_bf16 v[2:17], v[54:57], v[2:5], 0
	v_cndmask_b32_e64 v20, v28, 0, s[26:27]
	v_cndmask_b32_e64 v21, v29, 0, s[28:29]
	v_cndmask_b32_e64 v26, v30, 0, s[30:31]
	v_cndmask_b32_e64 v27, v31, 0, s[34:35]
	v_cvt_pk_bf16_f32 v18, v18, v19
	v_cvt_pk_bf16_f32 v19, v20, v21
	ds_read_b128 v[22:25], v199 offset:33280
	v_cvt_pk_bf16_f32 v20, v26, v27
	ds_read_b128 v[26:29], v199 offset:33312
	v_cndmask_b32_e64 v30, v32, 0, s[36:37]
	v_cndmask_b32_e64 v31, v33, 0, s[38:39]
	v_cvt_pk_bf16_f32 v21, v30, v31
	s_waitcnt lgkmcnt(1)
	v_pk_mul_f32 v[30:31], v[102:103], v[22:23]
	v_pk_mul_f32 v[32:33], v[104:105], v[24:25]
	v_mfma_f32_32x32x16_bf16 v[2:17], v[50:53], v[18:21], v[2:17]
	s_waitcnt lgkmcnt(0)
	v_mul_f32_e64 v190, v106, v26
	v_mul_f32_e64 v191, v107, v27
	v_mul_f32_e64 v192, v108, v28
	v_mul_f32_e64 v193, v109, v29
	v_cvt_pk_bf16_f32 v26, v30, v31
	v_cvt_pk_bf16_f32 v27, v32, v33
	v_cvt_pk_bf16_f32 v28, v190, v191
	v_cvt_pk_bf16_f32 v29, v192, v193
	ds_read_b128 v[18:21], v199 offset:33344
	ds_read_b128 v[22:25], v199 offset:33376
	v_mfma_f32_32x32x16_bf16 v[2:17], v[26:29], v[214:217], v[2:17]
	s_waitcnt lgkmcnt(1)
	v_mul_f32_e64 v18, v110, v18
	v_mul_f32_e64 v19, v111, v19
	v_mul_f32_e64 v20, v112, v20
	v_mul_f32_e64 v21, v113, v21
	s_waitcnt lgkmcnt(0)
	v_pk_mul_f32 v[22:23], v[114:115], v[22:23]
	v_cvt_pk_bf16_f32 v18, v18, v19
	v_cvt_pk_bf16_f32 v19, v20, v21
	v_cvt_pk_bf16_f32 v20, v22, v23
	v_pk_mul_f32 v[22:23], v[116:117], v[24:25]
	ds_read_b128 v[26:29], v199 offset:33440
	v_cvt_pk_bf16_f32 v21, v22, v23
	ds_read_b128 v[22:25], v199 offset:33408
	global_store_dwordx2 v[200:201], v[184:185], off offset:48
	v_mfma_f32_32x32x16_bf16 v[2:17], v[18:21], v[218:221], v[2:17]
	s_waitcnt lgkmcnt(0)
	v_mul_f32_e64 v30, v118, v22
	v_mul_f32_e64 v31, v119, v23
	v_mul_f32_e64 v32, v120, v24
	v_mul_f32_e64 v33, v121, v25
	ds_read_b128 v[18:21], v199 offset:33472
	ds_read_b128 v[22:25], v199 offset:33504
	v_pk_mul_f32 v[184:185], v[122:123], v[26:27]
	v_pk_mul_f32 v[186:187], v[124:125], v[28:29]
	v_cvt_pk_bf16_f32 v26, v30, v31
	v_cvt_pk_bf16_f32 v27, v32, v33
	v_cvt_pk_bf16_f32 v28, v184, v185
	v_cvt_pk_bf16_f32 v29, v186, v187
	s_waitcnt lgkmcnt(1)
	v_pk_mul_f32 v[18:19], v[126:127], v[18:19]
	v_pk_mul_f32 v[20:21], v[128:129], v[20:21]
	s_waitcnt lgkmcnt(0)
	v_pk_mul_f32 v[22:23], v[130:131], v[22:23]
	v_mad_i64_i32 v[30:31], s[62:63], v198, s70, v[182:183]
	v_cvt_pk_bf16_f32 v18, v18, v19
	v_cvt_pk_bf16_f32 v19, v20, v21
	v_cvt_pk_bf16_f32 v20, v22, v23
	v_pk_mul_f32 v[22:23], v[132:133], v[24:25]
	v_mfma_f32_32x32x16_bf16 v[2:17], v[26:29], v[222:225], v[2:17]
	v_cvt_pk_bf16_f32 v21, v22, v23
	ds_read_b128 v[22:25], v199 offset:33536
	ds_read_b128 v[26:29], v199 offset:33568
	global_load_dwordx2 v[192:193], v[30:31], off
	global_load_dwordx2 v[190:191], v[30:31], off offset:16
	global_load_dwordx2 v[186:187], v[30:31], off offset:32
	global_load_dwordx2 v[184:185], v[30:31], off offset:48
	s_waitcnt lgkmcnt(1)
	v_pk_mul_f32 v[30:31], v[196:197], v[22:23]
	v_pk_mul_f32 v[32:33], v[194:195], v[24:25]
	v_mfma_f32_32x32x16_bf16 v[2:17], v[18:21], v[238:241], v[2:17]
	s_waitcnt lgkmcnt(0)
	v_mul_f32_e64 v200, v100, v26
	v_mul_f32_e64 v201, v101, v27
	v_mul_f32_e64 v214, v98, v28
	v_mul_f32_e64 v215, v99, v29
	v_cvt_pk_bf16_f32 v26, v30, v31
	v_cvt_pk_bf16_f32 v27, v32, v33
	v_cvt_pk_bf16_f32 v28, v200, v201
	v_cvt_pk_bf16_f32 v29, v214, v215
	ds_read_b128 v[18:21], v199 offset:33600
	ds_read_b128 v[22:25], v199 offset:33632
	v_mfma_f32_32x32x16_bf16 v[2:17], v[26:29], v[46:49], v[2:17]
	s_waitcnt lgkmcnt(1)
	v_mul_f32_e64 v18, v58, v18
	v_mul_f32_e64 v19, v59, v19
	v_mul_f32_e64 v20, v60, v20
	v_mul_f32_e64 v21, v61, v21
	s_waitcnt lgkmcnt(0)
	v_pk_mul_f32 v[22:23], v[62:63], v[22:23]
	v_cvt_pk_bf16_f32 v18, v18, v19
	v_cvt_pk_bf16_f32 v19, v20, v21
	v_cvt_pk_bf16_f32 v20, v22, v23
	v_pk_mul_f32 v[22:23], v[64:65], v[24:25]
	s_nop 0
	v_cvt_pk_bf16_f32 v21, v22, v23
	ds_read_b128 v[22:25], v199 offset:33664
	ds_read_b128 v[26:29], v199 offset:33696
	v_mfma_f32_32x32x16_bf16 v[2:17], v[18:21], v[42:45], v[2:17]
	s_waitcnt lgkmcnt(1)
	v_mul_f32_e64 v30, v66, v22
	v_mul_f32_e64 v31, v67, v23
	v_mul_f32_e64 v32, v68, v24
	v_mul_f32_e64 v33, v69, v25
	s_waitcnt lgkmcnt(0)
	v_pk_mul_f32 v[42:43], v[70:71], v[26:27]
	v_pk_mul_f32 v[44:45], v[72:73], v[28:29]
	v_cvt_pk_bf16_f32 v26, v30, v31
	v_cvt_pk_bf16_f32 v27, v32, v33
	v_cvt_pk_bf16_f32 v28, v42, v43
	v_cvt_pk_bf16_f32 v29, v44, v45
	ds_read_b128 v[18:21], v199 offset:33728
	ds_read_b128 v[22:25], v199 offset:33760
	v_mfma_f32_32x32x16_bf16 v[2:17], v[26:29], v[38:41], v[2:17]
	s_waitcnt lgkmcnt(1)
	v_mul_f32_e64 v18, v74, v18
	v_mul_f32_e64 v19, v75, v19
	v_mul_f32_e64 v20, v76, v20
	v_mul_f32_e64 v21, v77, v21
	s_waitcnt lgkmcnt(0)
	v_pk_mul_f32 v[22:23], v[78:79], v[22:23]
	v_cvt_pk_bf16_f32 v18, v18, v19
	v_cvt_pk_bf16_f32 v19, v20, v21
	v_cvt_pk_bf16_f32 v20, v22, v23
	v_pk_mul_f32 v[22:23], v[80:81], v[24:25]
	s_nop 0
	v_cvt_pk_bf16_f32 v21, v22, v23
	s_nop 1
	v_mfma_f32_32x32x16_bf16 v[2:17], v[18:21], v[34:37], v[2:17]
	s_nop 11
	v_mul_f32_e32 v18, v3, v3
	v_fmac_f32_e32 v18, v2, v2
	v_fmac_f32_e32 v18, v4, v4
	v_fmac_f32_e32 v18, v5, v5
	v_fmac_f32_e32 v18, v6, v6
	v_fmac_f32_e32 v18, v7, v7
	v_fmac_f32_e32 v18, v8, v8
	v_fmac_f32_e32 v18, v9, v9
	v_fmac_f32_e32 v18, v10, v10
	v_fmac_f32_e32 v18, v11, v11
	v_fmac_f32_e32 v18, v12, v12
	v_fmac_f32_e32 v18, v13, v13
	v_fmac_f32_e32 v18, v14, v14
	v_fmac_f32_e32 v18, v15, v15
	v_fmac_f32_e32 v18, v16, v16
	v_fmac_f32_e32 v18, v17, v17
	ds_bpermute_b32 v19, v210, v18
	s_and_saveexec_b64 s[62:63], s[4:5]
	s_cbranch_execz .LBB0_988
	s_and_b32 s65, s64, 0x80
	s_waitcnt lgkmcnt(0)
	v_add_f32_e32 v18, v18, v19
	v_lshl_add_u32 v19, s65, 2, v211
	ds_write_b32 v19, v18
	s_branch .LBB0_988
